# ERES1 loop (4 phases): row loads of both rows and both partial-sum loads now issue back to back (hipcc had a vmcnt(0) before each group: three dependent round trips per iteration)
# speedup vs baseline: 1.0092x; 1.0038x over previous
.LBB0_107:
	s_andn2_saveexec_b64 s[44:45], s[44:45]
	s_cbranch_execz .LBB0_111
	v_mov_b32_e32 v50, 0
	s_and_saveexec_b64 s[46:47], s[40:41]
	s_cbranch_execz .LBB0_110
	v_ashrrev_i32_e32 v67, 31, v66
	s_waitcnt lgkmcnt(0)
	v_lshlrev_b64 v[18:19], 6, v[66:67]
	v_lshl_add_u64 v[18:19], v[56:57], 0, v[18:19]
	global_load_dword v50, v[18:19], off

.LBB0_111:
	s_or_b64 exec, exec, s[44:45]
	v_ashrrev_i32_e32 v67, 31, v66
	s_waitcnt lgkmcnt(0)
	v_lshlrev_b64 v[18:19], 11, v[66:67]
	v_lshl_add_u64 v[68:69], v[60:61], 0, v[18:19]
	v_lshl_add_u64 v[18:19], v[62:63], 0, v[18:19]
	global_load_dwordx4 v[46:49], v[68:69], off
	global_load_dwordx4 v[38:41], v[68:69], off offset:1024
	global_load_dwordx4 v[42:45], v[18:19], off
	global_load_dwordx4 v[34:37], v[18:19], off offset:1024
	v_add_u32_e32 v64, s16, v66
	v_cmp_gt_i32_e64 s[46:47], s15, v64
	s_nop 1
	v_cndmask_b32_e64 v18, v66, v64, s[46:47]
	v_cmp_lt_i32_e32 vcc, s4, v18
	s_and_saveexec_b64 s[18:19], vcc
	s_xor_b64 s[44:45], exec, s[18:19]
	s_cbranch_execz .LBB0_115
	v_mov_b32_e32 v65, 0
	s_and_saveexec_b64 s[50:51], s[38:39]
	s_cbranch_execz .LBB0_114
	v_lshl_add_u32 v20, v18, 5, v55
	v_mov_b32_e32 v21, v1
	v_lshl_add_u64 v[20:21], v[20:21], 2, s[76:77]
	global_load_dword v65, v[20:21], off

.LBB0_115:
	s_andn2_saveexec_b64 s[44:45], s[44:45]
	s_cbranch_execz .LBB0_119
	v_mov_b32_e32 v65, 0
	s_and_saveexec_b64 s[50:51], s[40:41]
	s_cbranch_execz .LBB0_118
	v_ashrrev_i32_e32 v19, 31, v18
	v_lshlrev_b64 v[20:21], 6, v[18:19]
	v_lshl_add_u64 v[20:21], v[56:57], 0, v[20:21]
	global_load_dword v65, v[20:21], off

.LBB0_143:
	s_nop 0
	s_nop 0
	s_or_b64 exec, exec, s[62:63]
	s_mov_b64 s[40:41], 0
	s_mov_b32 s20, 0xb000
